# attention A: lazy-rescale test on the raw tile max against a per-query threshold refreshed on rescale (two VALU fewer per tile)
# baseline (speedup 1.0000x reference)
.LBB0_342:
	s_and_b64 s[24:25], s[36:37], exec
	s_cselect_b32 s54, s44, s45
	s_ashr_i32 s55, s54, 6
	s_sub_i32 s4, 7, s55
	s_lshl_b32 s24, s4, 8
	s_add_i32 s24, s24, s40
	s_lshl_b32 s53, s4, 2
	s_lshl_b32 s4, s54, 9
	s_add_i32 s52, s53, s41
	s_and_b32 s26, s4, 0x7800
	s_ashr_i32 s4, s24, 31
	s_add_u32 s57, s24, s26
	s_addc_u32 s58, s4, 0
	s_lshl_b32 s4, s54, 7
	s_mul_i32 s24, s58, 0x1800
	s_mul_hi_u32 s25, s57, 0x1800
	s_and_b32 s4, s4, 0x180
	s_add_i32 s25, s25, s24
	s_mul_i32 s24, s57, 0x1800
	s_add_u32 s24, s10, s24
	s_addc_u32 s25, s11, s25
	s_lshl_b32 s4, s4, 1
	s_add_u32 s24, s24, s4
	s_addc_u32 s25, s25, 0
	v_lshl_add_u64 v[2:3], s[24:25], 0, v[132:133]
	v_lshl_add_u64 v[128:129], v[2:3], 0, v[134:135]
	global_load_dwordx4 v[112:115], v[128:129], off
	global_load_dwordx4 v[116:119], v[128:129], off offset:32
	global_load_dwordx4 v[120:123], v[128:129], off offset:64
	global_load_dwordx4 v[124:127], v[128:129], off offset:96
	s_mul_i32 s56, s26, 0x1800
	s_add_u32 s25, s10, s56
	s_addc_u32 s26, s11, 0
	s_add_u32 s30, s25, s4
	s_addc_u32 s31, s26, 0
	s_add_u32 s28, s30, 0x400
	s_addc_u32 s29, s31, 0
	v_readfirstlane_b32 s24, v215
	s_add_u32 s26, s30, 0x800
	s_addc_u32 s27, s31, 0
	s_lshr_b32 s24, s24, 6
	s_lshl_b32 s25, s24, 3
	v_or_b32_e32 v0, s25, v172
	v_or_b32_e32 v2, s25, v184
	v_lshrrev_b32_e32 v4, 1, v0
	v_mul_lo_u32 v6, v2, s42
	v_xor_b32_e32 v7, v4, v215
	v_or_b32_e32 v2, v6, v194
	v_add_u32_e32 v4, v6, v195
	v_lshlrev_b32_e32 v6, 3, v7
	v_mul_lo_u32 v0, v0, s42
	v_and_b32_e32 v6, 56, v6
	s_lshl_b32 s59, s24, 10
	v_or_b32_e32 v0, v6, v0
	v_mov_b32_e32 v3, v1
	s_lshl_b32 s60, s24, 11
	s_add_i32 s38, s59, 0
	v_lshl_add_u64 v[12:13], v[0:1], 1, s[30:31]
	s_add_i32 s25, s60, 0
	v_lshl_add_u64 v[8:9], v[2:3], 1, s[30:31]
	v_lshl_add_u64 v[12:13], v[12:13], 0, s[6:7]
	s_mov_b32 m0, s38
	v_mov_b32_e32 v5, v1
	v_lshl_add_u64 v[8:9], v[8:9], 0, s[12:13]
	v_lshl_add_u64 v[10:11], v[4:5], 1, s[26:27]
	s_add_i32 s53, s53, 4
	s_barrier
	global_load_lds_dwordx4 v[12:13], off
	s_add_i32 m0, s25, 0x2000
	s_nop 0
	global_load_lds_dwordx4 v[8:9], off
	s_add_i32 m0, s25, 0x2400
	s_cmp_lt_i32 s55, 8
	global_load_lds_dwordx4 v[10:11], off
	s_cselect_b64 s[34:35], -1, 0
	s_cmp_gt_i32 s55, 7
	s_cbranch_scc1 .LBB0_359
	s_add_u32 s62, s26, 0x60000
	v_lshl_add_u64 v[12:13], v[0:1], 1, s[28:29]
	s_addc_u32 s63, s27, 0
	v_lshlrev_b64 v[2:3], 1, v[2:3]
	v_lshl_add_u64 v[14:15], v[12:13], 0, s[14:15]
	s_add_i32 m0, s38, 0x6000
	v_lshl_add_u64 v[10:11], s[62:63], 0, v[2:3]
	global_load_lds_dwordx4 v[14:15], off
	s_add_i32 m0, s25, 0x8000
	v_lshlrev_b64 v[4:5], 1, v[4:5]
	global_load_lds_dwordx4 v[10:11], off
	s_add_i32 m0, s25, 0x8400
	v_lshl_add_u64 v[8:9], s[62:63], 0, v[4:5]
	s_add_u32 s62, s26, 0xc0000
	global_load_lds_dwordx4 v[8:9], off
	s_addc_u32 s63, s27, 0
	v_lshl_add_u64 v[8:9], v[12:13], 0, s[16:17]
	s_add_i32 m0, s38, 0xc000
	v_lshl_add_u64 v[2:3], s[62:63], 0, v[2:3]
	global_load_lds_dwordx4 v[8:9], off
	s_add_i32 m0, s25, 0xe000
	v_lshl_add_u64 v[4:5], s[62:63], 0, v[4:5]
	global_load_lds_dwordx4 v[2:3], off
	s_add_i32 m0, s25, 0xe400
	s_mul_i32 s38, s24, 0x6000
	global_load_lds_dwordx4 v[4:5], off
	s_and_b32 s24, s54, 3
	s_lshl_b32 s61, s55, 2
	v_add_u32_e32 v0, s38, v196
	s_lshl_b32 s24, s24, 8
	v_lshl_add_u64 v[130:131], v[0:1], 1, v[138:139]
	s_add_u32 s24, s56, s24
	v_add_u32_e32 v0, s38, v197
	s_addc_u32 s25, 0, 0
	v_lshl_add_u64 v[146:147], v[0:1], 1, v[138:139]
	v_add3_u32 v0, v188, s38, v6
	v_mov_b32_e32 v14, v1
	v_mov_b32_e32 v15, v1
	s_add_u32 s24, s50, s24
	v_lshl_add_u64 v[148:149], v[0:1], 1, v[140:141]
	v_mov_b32_e32 v0, v1
	v_mov_b32_e32 v2, v1
	v_mov_b32_e32 v3, v1
	v_mov_b32_e32 v4, v1
	v_mov_b32_e32 v5, v1
	v_mov_b32_e32 v6, v1
	v_mov_b32_e32 v7, v1
	v_mov_b32_e32 v8, v1
	v_mov_b32_e32 v9, v1
	v_mov_b32_e32 v10, v1
	v_mov_b32_e32 v11, v1
	v_mov_b32_e32 v12, v1
	v_mov_b32_e32 v13, v1
	v_mov_b64_e32 v[30:31], v[14:15]
	v_mov_b64_e32 v[46:47], v[14:15]
	v_mov_b64_e32 v[62:63], v[14:15]
	v_mov_b64_e32 v[78:79], v[14:15]
	s_addc_u32 s25, s51, s25
	s_sub_i32 s62, 31, s61
	s_mov_b32 s63, 0
	v_mov_b32_e32 v150, 0
	v_mov_b32_e32 v151, 0xf149f2ca
	v_mov_b32_e32 v242, 0xf28bfadf
	v_mov_b64_e32 v[28:29], v[12:13]
	v_mov_b64_e32 v[26:27], v[10:11]
	v_mov_b64_e32 v[24:25], v[8:9]
	v_mov_b64_e32 v[22:23], v[6:7]
	v_mov_b64_e32 v[20:21], v[4:5]
	v_mov_b64_e32 v[18:19], v[2:3]
	v_mov_b64_e32 v[16:17], v[0:1]
	v_mov_b64_e32 v[44:45], v[12:13]
	v_mov_b64_e32 v[42:43], v[10:11]
	v_mov_b64_e32 v[40:41], v[8:9]
	v_mov_b64_e32 v[38:39], v[6:7]
	v_mov_b64_e32 v[36:37], v[4:5]
	v_mov_b64_e32 v[34:35], v[2:3]
	v_mov_b64_e32 v[32:33], v[0:1]
	v_mov_b64_e32 v[60:61], v[12:13]
	v_mov_b64_e32 v[58:59], v[10:11]
	v_mov_b64_e32 v[56:57], v[8:9]
	v_mov_b64_e32 v[54:55], v[6:7]
	v_mov_b64_e32 v[52:53], v[4:5]
	v_mov_b64_e32 v[50:51], v[2:3]
	v_mov_b64_e32 v[48:49], v[0:1]
	v_mov_b64_e32 v[76:77], v[12:13]
	v_mov_b64_e32 v[74:75], v[10:11]
	v_mov_b64_e32 v[72:73], v[8:9]
	v_mov_b64_e32 v[70:71], v[6:7]
	v_mov_b64_e32 v[68:69], v[4:5]
	v_mov_b64_e32 v[66:67], v[2:3]
	v_mov_b64_e32 v[64:65], v[0:1]
	s_branch .LBB0_346

.LBB0_355:
	s_cmp_gt_i32 s63, s52
	s_cbranch_scc1 .LBB0_345
	s_and_b32 s38, s63, 3
	s_mulk_i32 s38, 0x6000
	s_add_i32 s38, s38, 0
	v_add3_u32 v14, s38, v174, v173
	v_add3_u32 v15, s38, v174, v177
	ds_read_b128 v[2:5], v14
	ds_read_b128 v[6:9], v14 offset:4096
	ds_read_b128 v[10:13], v15
	ds_read_b128 v[152:155], v15 offset:4096
	v_add3_u32 v14, s38, v174, v179
	v_add3_u32 v15, s38, v174, v180
	ds_read_b128 v[156:159], v14
	ds_read_b128 v[160:163], v14 offset:4096
	ds_read_b128 v[244:247], v15
	ds_read_b128 v[248:251], v15 offset:4096
	s_waitcnt lgkmcnt(6)
	v_mfma_f32_32x32x16_bf16 v[96:111], v[2:5], v[112:115], 0
	v_mfma_f32_32x32x16_bf16 v[80:95], v[6:9], v[112:115], 0
	s_waitcnt lgkmcnt(4)
	v_mfma_f32_32x32x16_bf16 v[96:111], v[10:13], v[116:119], v[96:111]
	v_mfma_f32_32x32x16_bf16 v[80:95], v[152:155], v[116:119], v[80:95]
	s_waitcnt lgkmcnt(2)
	v_mfma_f32_32x32x16_bf16 v[96:111], v[156:159], v[120:123], v[96:111]
	v_mfma_f32_32x32x16_bf16 v[80:95], v[160:163], v[120:123], v[80:95]
	s_waitcnt lgkmcnt(0)
	v_mfma_f32_32x32x16_bf16 v[80:95], v[248:251], v[124:127], v[80:95]
	v_mfma_f32_32x32x16_bf16 v[96:111], v[244:247], v[124:127], v[96:111]
	s_nop 10
	v_max3_f32 v0, v80, v81, v82
	v_max3_f32 v2, v83, v84, v85
	v_max3_f32 v3, v86, v87, v88
	v_max3_f32 v4, v89, v90, v91
	v_max3_f32 v0, v0, v92, v93
	v_max3_f32 v2, v2, v94, v95
	v_max3_f32 v3, v3, v96, v97
	v_max3_f32 v4, v4, v98, v99
	v_max3_f32 v0, v0, v100, v101
	v_max3_f32 v2, v2, v102, v103
	v_max3_f32 v3, v3, v104, v105
	v_max3_f32 v4, v4, v106, v107
	v_max3_f32 v0, v0, v108, v109
	v_max3_f32 v2, v2, v110, v111
	v_max3_f32 v0, v0, v3, v4
	v_max_f32_e32 v0, v0, v2
	v_mov_b32_e32 v2, v0
	s_nop 1
	v_permlane32_swap_b32_e32 v0, v2
	v_max_f32_e32 v0, v0, v2
	v_cmp_gt_f32_e32 vcc, v0, v242
	s_cbranch_vccz .LBB0_344
	v_mul_f32_e32 v0, 0x3e38aa3b, v0
	v_max_f32_e32 v0, v0, v0
	v_max_f32_e32 v2, v151, v151
	v_max_f32_e32 v2, v2, v0
	v_sub_f32_e32 v0, v151, v2
	v_exp_f32_e32 v0, v0
	v_mov_b32_e32 v151, v2
	v_add_f32_e32 v2, 0x41000000, v2
	v_mul_f32_e32 v242, 0x40b17218, v2
	v_pk_mul_f32 v[78:79], v[0:1], v[78:79] op_sel_hi:[0,1]
	v_pk_mul_f32 v[76:77], v[0:1], v[76:77] op_sel_hi:[0,1]
	v_pk_mul_f32 v[74:75], v[0:1], v[74:75] op_sel_hi:[0,1]
	v_pk_mul_f32 v[72:73], v[0:1], v[72:73] op_sel_hi:[0,1]
	v_pk_mul_f32 v[70:71], v[0:1], v[70:71] op_sel_hi:[0,1]
	v_pk_mul_f32 v[68:69], v[0:1], v[68:69] op_sel_hi:[0,1]
	v_pk_mul_f32 v[66:67], v[0:1], v[66:67] op_sel_hi:[0,1]
	v_pk_mul_f32 v[64:65], v[0:1], v[64:65] op_sel_hi:[0,1]
	v_pk_mul_f32 v[62:63], v[0:1], v[62:63] op_sel_hi:[0,1]
	v_pk_mul_f32 v[60:61], v[0:1], v[60:61] op_sel_hi:[0,1]
	v_pk_mul_f32 v[58:59], v[0:1], v[58:59] op_sel_hi:[0,1]
	v_pk_mul_f32 v[56:57], v[0:1], v[56:57] op_sel_hi:[0,1]
	v_pk_mul_f32 v[54:55], v[0:1], v[54:55] op_sel_hi:[0,1]
	v_pk_mul_f32 v[52:53], v[0:1], v[52:53] op_sel_hi:[0,1]
	v_pk_mul_f32 v[50:51], v[0:1], v[50:51] op_sel_hi:[0,1]
	v_pk_mul_f32 v[48:49], v[0:1], v[48:49] op_sel_hi:[0,1]
	v_pk_mul_f32 v[46:47], v[0:1], v[46:47] op_sel_hi:[0,1]
	v_pk_mul_f32 v[44:45], v[0:1], v[44:45] op_sel_hi:[0,1]
	v_pk_mul_f32 v[42:43], v[0:1], v[42:43] op_sel_hi:[0,1]
	v_pk_mul_f32 v[40:41], v[0:1], v[40:41] op_sel_hi:[0,1]
	v_pk_mul_f32 v[38:39], v[0:1], v[38:39] op_sel_hi:[0,1]
	v_pk_mul_f32 v[36:37], v[0:1], v[36:37] op_sel_hi:[0,1]
	v_pk_mul_f32 v[34:35], v[0:1], v[34:35] op_sel_hi:[0,1]
	v_pk_mul_f32 v[32:33], v[0:1], v[32:33] op_sel_hi:[0,1]
	v_pk_mul_f32 v[30:31], v[0:1], v[30:31] op_sel_hi:[0,1]
	v_pk_mul_f32 v[28:29], v[0:1], v[28:29] op_sel_hi:[0,1]
	v_pk_mul_f32 v[26:27], v[0:1], v[26:27] op_sel_hi:[0,1]
	v_pk_mul_f32 v[24:25], v[0:1], v[24:25] op_sel_hi:[0,1]
	v_pk_mul_f32 v[22:23], v[0:1], v[22:23] op_sel_hi:[0,1]
	v_pk_mul_f32 v[20:21], v[0:1], v[20:21] op_sel_hi:[0,1]
	v_pk_mul_f32 v[18:19], v[0:1], v[18:19] op_sel_hi:[0,1]
	v_pk_mul_f32 v[16:17], v[0:1], v[16:17] op_sel_hi:[0,1]
	v_mul_f32_e32 v150, v150, v0
	s_branch .LBB0_344

.LBB0_360:
	s_waitcnt lgkmcnt(0)
	s_barrier
	global_load_dwordx4 v[112:115], v[128:129], off offset:128
	global_load_dwordx4 v[116:119], v[128:129], off offset:160
	global_load_dwordx4 v[120:123], v[128:129], off offset:192
	global_load_dwordx4 v[124:127], v[128:129], off offset:224
	s_lshl_b32 s68, s92, 3
	v_mov_b32_e32 v81, 0
	v_or_b32_e32 v80, s68, v172
	v_lshrrev_b32_e32 v82, 1, v80
	v_xor_b32_e32 v82, v82, v215
	v_lshlrev_b32_e32 v82, 3, v82
	v_and_b32_e32 v86, 56, v82
	v_mul_lo_u32 v80, v80, s42
	v_or_b32_e32 v82, s68, v184
	v_or_b32_e32 v80, v86, v80
	s_lshl_b32 s69, s92, 10
	v_mul_lo_u32 v83, v82, s42
	v_lshl_add_u64 v[88:89], v[80:81], 1, s[30:31]
	v_or_b32_e32 v82, v83, v194
	v_add_u32_e32 v84, v83, v195
	v_lshl_add_u64 v[88:89], v[88:89], 0, s[18:19]
	s_mov_b32 m0, s69
	s_lshl_b32 s70, s92, 11
	v_mov_b32_e32 v83, 0
	global_load_lds_dwordx4 v[88:89], off
	v_lshl_add_u64 v[88:89], v[82:83], 1, s[30:31]
	s_add_i32 m0, s70, 0x2000
	v_lshl_add_u64 v[88:89], v[88:89], 0, s[12:13]
	v_mov_b32_e32 v85, 0
	global_load_lds_dwordx4 v[88:89], off
	v_lshl_add_u64 v[88:89], v[84:85], 1, s[26:27]
	s_add_i32 m0, s70, 0x2400
	s_nop 0
	global_load_lds_dwordx4 v[88:89], off
	s_add_u32 s72, s26, 0x60000
	v_lshl_add_u64 v[92:93], v[80:81], 1, s[28:29]
	s_addc_u32 s73, s27, 0
	v_lshlrev_b64 v[82:83], 1, v[82:83]
	v_lshl_add_u64 v[94:95], v[92:93], 0, s[20:21]
	s_add_i32 m0, s69, 0x6000
	v_lshl_add_u64 v[90:91], s[72:73], 0, v[82:83]
	global_load_lds_dwordx4 v[94:95], off
	s_add_i32 m0, s70, 0x8000
	v_lshlrev_b64 v[84:85], 1, v[84:85]
	global_load_lds_dwordx4 v[90:91], off
	s_add_i32 m0, s70, 0x8400
	v_lshl_add_u64 v[88:89], s[72:73], 0, v[84:85]
	s_add_u32 s74, s26, 0xc0000
	global_load_lds_dwordx4 v[88:89], off
	s_addc_u32 s75, s27, 0
	v_lshl_add_u64 v[88:89], v[92:93], 0, s[22:23]
	s_add_i32 m0, s69, 0xc000
	v_lshl_add_u64 v[82:83], s[74:75], 0, v[82:83]
	global_load_lds_dwordx4 v[88:89], off
	s_add_i32 m0, s70, 0xe000
	v_lshl_add_u64 v[84:85], s[74:75], 0, v[84:85]
	global_load_lds_dwordx4 v[82:83], off
	s_add_i32 m0, s70, 0xe400
	s_nop 0
	global_load_lds_dwordx4 v[84:85], off
	v_and_b32_e32 v2, 64, v193
	v_xor_b32_e32 v0, 32, v193
	v_add_u32_e32 v2, 64, v2
	v_cmp_lt_i32_e32 vcc, v0, v2
	s_xor_b64 s[24:25], s[36:37], -1
	v_mov_b32_e32 v3, s58
	v_cndmask_b32_e32 v0, v193, v0, vcc
	v_lshlrev_b32_e32 v198, 2, v0
	ds_bpermute_b32 v0, v198, v150
	v_or_b32_e32 v2, s57, v178
	v_lshlrev_b64 v[2:3], 11, v[2:3]
	v_lshl_add_u64 v[2:3], s[90:91], 0, v[2:3]
	v_lshl_add_u64 v[2:3], v[2:3], 0, s[4:5]
	s_waitcnt lgkmcnt(0)
	v_add_f32_e32 v0, v150, v0
	v_div_scale_f32 v4, s[36:37], v0, v0, 1.0
	v_rcp_f32_e32 v5, v4
	v_readfirstlane_b32 s4, v215
	s_lshr_b32 s37, s4, 6
	s_lshl_b32 s4, s37, 3
	v_fma_f32 v6, -v4, v5, 1.0
	v_fmac_f32_e32 v5, v6, v5
	v_div_scale_f32 v6, vcc, 1.0, v0, 1.0
	v_mul_f32_e32 v7, v6, v5
	v_fma_f32 v8, -v4, v7, v6
	v_fmac_f32_e32 v7, v8, v5
	v_fma_f32 v4, -v4, v7, v6
	v_div_fmas_f32 v4, v4, v5, v7
	v_div_fixup_f32 v0, v4, v0, 1.0
	v_pk_mul_f32 v[4:5], v[64:65], v[0:1] op_sel_hi:[1,0]
	v_pk_mul_f32 v[6:7], v[66:67], v[0:1] op_sel_hi:[1,0]
	v_pk_mul_f32 v[8:9], v[68:69], v[0:1] op_sel_hi:[1,0]
	v_pk_mul_f32 v[10:11], v[70:71], v[0:1] op_sel_hi:[1,0]
	v_pk_mul_f32 v[12:13], v[72:73], v[0:1] op_sel_hi:[1,0]
	v_pk_mul_f32 v[14:15], v[74:75], v[0:1] op_sel_hi:[1,0]
	v_pk_mul_f32 v[64:65], v[76:77], v[0:1] op_sel_hi:[1,0]
	v_pk_mul_f32 v[66:67], v[78:79], v[0:1] op_sel_hi:[1,0]
	v_pk_mul_f32 v[48:49], v[0:1], v[48:49] op_sel_hi:[0,1]
	v_pk_mul_f32 v[50:51], v[0:1], v[50:51] op_sel_hi:[0,1]
	v_pk_mul_f32 v[52:53], v[0:1], v[52:53] op_sel_hi:[0,1]
	v_pk_mul_f32 v[54:55], v[0:1], v[54:55] op_sel_hi:[0,1]
	v_pk_mul_f32 v[56:57], v[0:1], v[56:57] op_sel_hi:[0,1]
	v_pk_mul_f32 v[58:59], v[0:1], v[58:59] op_sel_hi:[0,1]
	v_pk_mul_f32 v[60:61], v[0:1], v[60:61] op_sel_hi:[0,1]
	v_pk_mul_f32 v[62:63], v[0:1], v[62:63] op_sel_hi:[0,1]
	v_pk_mul_f32 v[32:33], v[0:1], v[32:33] op_sel_hi:[0,1]
	v_pk_mul_f32 v[34:35], v[0:1], v[34:35] op_sel_hi:[0,1]
	v_pk_mul_f32 v[36:37], v[0:1], v[36:37] op_sel_hi:[0,1]
	v_pk_mul_f32 v[38:39], v[0:1], v[38:39] op_sel_hi:[0,1]
	v_pk_mul_f32 v[40:41], v[0:1], v[40:41] op_sel_hi:[0,1]
	v_pk_mul_f32 v[42:43], v[0:1], v[42:43] op_sel_hi:[0,1]
	v_pk_mul_f32 v[44:45], v[0:1], v[44:45] op_sel_hi:[0,1]
	v_pk_mul_f32 v[46:47], v[0:1], v[46:47] op_sel_hi:[0,1]
	v_pk_mul_f32 v[16:17], v[0:1], v[16:17] op_sel_hi:[0,1]
	v_pk_mul_f32 v[18:19], v[0:1], v[18:19] op_sel_hi:[0,1]
	v_pk_mul_f32 v[20:21], v[0:1], v[20:21] op_sel_hi:[0,1]
	v_pk_mul_f32 v[22:23], v[0:1], v[22:23] op_sel_hi:[0,1]
	v_pk_mul_f32 v[24:25], v[0:1], v[24:25] op_sel_hi:[0,1]
	v_pk_mul_f32 v[26:27], v[0:1], v[26:27] op_sel_hi:[0,1]
	v_pk_mul_f32 v[28:29], v[0:1], v[28:29] op_sel_hi:[0,1]
	v_pk_mul_f32 v[30:31], v[0:1], v[30:31] op_sel_hi:[0,1]
	v_lshlrev_b32_e32 v0, 1, v181
	v_lshl_add_u64 v[146:147], v[2:3], 0, v[0:1]
	v_cvt_pk_bf16_f32 v2, v4, v5
	v_cvt_pk_bf16_f32 v3, v6, v7
	global_store_dwordx2 v[146:147], v[2:3], off
	v_cvt_pk_bf16_f32 v2, v8, v9
	v_cvt_pk_bf16_f32 v3, v10, v11
	global_store_dwordx2 v[146:147], v[2:3], off offset:16
	v_cvt_pk_bf16_f32 v2, v12, v13
	v_cvt_pk_bf16_f32 v3, v14, v15
	global_store_dwordx2 v[146:147], v[2:3], off offset:32
	v_cvt_pk_bf16_f32 v2, v64, v65
	v_cvt_pk_bf16_f32 v3, v66, v67
	global_store_dwordx2 v[146:147], v[2:3], off offset:48
	v_cvt_pk_bf16_f32 v2, v48, v49
	v_cvt_pk_bf16_f32 v3, v50, v51
	global_store_dwordx2 v[146:147], v[2:3], off offset:64
	v_cvt_pk_bf16_f32 v2, v52, v53
	v_cvt_pk_bf16_f32 v3, v54, v55
	global_store_dwordx2 v[146:147], v[2:3], off offset:80
	v_cvt_pk_bf16_f32 v2, v56, v57
	v_cvt_pk_bf16_f32 v3, v58, v59
	global_store_dwordx2 v[146:147], v[2:3], off offset:96
	v_cvt_pk_bf16_f32 v2, v60, v61
	v_cvt_pk_bf16_f32 v3, v62, v63
	global_store_dwordx2 v[146:147], v[2:3], off offset:112
	v_cvt_pk_bf16_f32 v2, v32, v33
	v_cvt_pk_bf16_f32 v3, v34, v35
	global_store_dwordx2 v[146:147], v[2:3], off offset:128
	v_cvt_pk_bf16_f32 v2, v36, v37
	v_cvt_pk_bf16_f32 v3, v38, v39
	global_store_dwordx2 v[146:147], v[2:3], off offset:144
	v_cvt_pk_bf16_f32 v2, v40, v41
	v_cvt_pk_bf16_f32 v3, v42, v43
	global_store_dwordx2 v[146:147], v[2:3], off offset:160
	v_cvt_pk_bf16_f32 v2, v44, v45
	v_cvt_pk_bf16_f32 v3, v46, v47
	global_store_dwordx2 v[146:147], v[2:3], off offset:176
	v_cvt_pk_bf16_f32 v2, v16, v17
	v_cvt_pk_bf16_f32 v3, v18, v19
	global_store_dwordx2 v[146:147], v[2:3], off offset:192
	v_cvt_pk_bf16_f32 v2, v20, v21
	v_cvt_pk_bf16_f32 v3, v22, v23
	global_store_dwordx2 v[146:147], v[2:3], off offset:208
	v_cvt_pk_bf16_f32 v2, v24, v25
	v_cvt_pk_bf16_f32 v3, v26, v27
	global_store_dwordx2 v[146:147], v[2:3], off offset:224
	v_cvt_pk_bf16_f32 v2, v28, v29
	v_cvt_pk_bf16_f32 v3, v30, v31
	global_store_dwordx2 v[146:147], v[2:3], off offset:240
	v_or_b32_e32 v0, s4, v172
	v_lshrrev_b32_e32 v2, 1, v0
	v_xor_b32_e32 v2, v2, v215
	v_lshlrev_b32_e32 v2, 3, v2
	v_and_b32_e32 v6, 56, v2
	v_mul_lo_u32 v0, v0, s42
	v_or_b32_e32 v2, s4, v184
	v_or_b32_e32 v0, v6, v0
	s_lshl_b32 s4, s37, 10
	v_mul_lo_u32 v3, v2, s42
	v_lshl_add_u64 v[8:9], v[0:1], 1, s[30:31]
	s_add_i32 s39, s4, 0
	v_or_b32_e32 v2, v3, v194
	v_add_u32_e32 v4, v3, v195
	s_waitcnt vmcnt(0)
	s_waitcnt vmcnt(0)
	v_lshl_add_u64 v[8:9], v[8:9], 0, s[18:19]
	s_mov_b32 m0, s39
	s_lshl_b32 s36, s37, 11
	v_mov_b32_e32 v3, v1
	s_add_i32 s38, s36, 0
	v_lshl_add_u64 v[8:9], v[2:3], 1, s[30:31]
	s_add_i32 m0, s38, 0x2000
	v_lshl_add_u64 v[8:9], v[8:9], 0, s[12:13]
	v_mov_b32_e32 v5, v1
	v_lshl_add_u64 v[8:9], v[4:5], 1, s[26:27]
	s_add_i32 m0, s38, 0x2400
	s_andn2_b64 vcc, exec, s[34:35]
	s_cbranch_vccnz .LBB0_340
	s_add_u32 s30, s26, 0x60000
	v_lshl_add_u64 v[12:13], v[0:1], 1, s[28:29]
	s_addc_u32 s31, s27, 0
	v_lshlrev_b64 v[2:3], 1, v[2:3]
	v_lshl_add_u64 v[14:15], v[12:13], 0, s[20:21]
	s_add_i32 m0, s39, 0x6000
	v_lshl_add_u64 v[10:11], s[30:31], 0, v[2:3]
	s_add_i32 m0, s38, 0x8000
	v_lshlrev_b64 v[4:5], 1, v[4:5]
	s_add_i32 m0, s38, 0x8400
	v_lshl_add_u64 v[8:9], s[30:31], 0, v[4:5]
	s_add_u32 s26, s26, 0xc0000
	s_addc_u32 s27, s27, 0
	v_lshl_add_u64 v[8:9], v[12:13], 0, s[22:23]
	s_add_i32 m0, s39, 0xc000
	v_lshl_add_u64 v[2:3], s[26:27], 0, v[2:3]
	s_add_i32 m0, s38, 0xe000
	v_lshl_add_u64 v[4:5], s[26:27], 0, v[4:5]
	s_add_i32 m0, s38, 0xe400
	s_mulk_i32 s37, 0x6000
	s_and_b32 s26, s54, 3
	s_lshl_b32 s30, s55, 2
	v_add_u32_e32 v0, s37, v196
	s_lshl_b32 s26, s26, 8
	v_lshl_add_u64 v[128:129], v[0:1], 1, v[138:139]
	s_add_u32 s26, s56, s26
	v_add_u32_e32 v0, s37, v197
	s_addc_u32 s27, 0, 0
	v_lshl_add_u64 v[130:131], v[0:1], 1, v[138:139]
	v_add3_u32 v0, v188, s37, v6
	v_mov_b32_e32 v14, v1
	v_mov_b32_e32 v15, v1
	s_add_u32 s26, s50, s26
	v_lshl_add_u64 v[148:149], v[0:1], 1, v[142:143]
	v_mov_b32_e32 v0, v1
	v_mov_b32_e32 v2, v1
	v_mov_b32_e32 v3, v1
	v_mov_b32_e32 v4, v1
	v_mov_b32_e32 v5, v1
	v_mov_b32_e32 v6, v1
	v_mov_b32_e32 v7, v1
	v_mov_b32_e32 v8, v1
	v_mov_b32_e32 v9, v1
	v_mov_b32_e32 v10, v1
	v_mov_b32_e32 v11, v1
	v_mov_b32_e32 v12, v1
	v_mov_b32_e32 v13, v1
	v_mov_b64_e32 v[78:79], v[14:15]
	v_mov_b64_e32 v[62:63], v[14:15]
	v_mov_b64_e32 v[46:47], v[14:15]
	v_mov_b64_e32 v[30:31], v[14:15]
	s_addc_u32 s27, s51, s27
	s_sub_i32 s31, 31, s30
	s_mov_b32 s34, 0
	v_mov_b32_e32 v154, 0
	v_mov_b32_e32 v150, 0xf149f2ca
	v_mov_b32_e32 v242, 0xf28bfadf
	v_mov_b64_e32 v[76:77], v[12:13]
	v_mov_b64_e32 v[74:75], v[10:11]
	v_mov_b64_e32 v[72:73], v[8:9]
	v_mov_b64_e32 v[70:71], v[6:7]
	v_mov_b64_e32 v[68:69], v[4:5]
	v_mov_b64_e32 v[66:67], v[2:3]
	v_mov_b64_e32 v[64:65], v[0:1]
	v_mov_b64_e32 v[60:61], v[12:13]
	v_mov_b64_e32 v[58:59], v[10:11]
	v_mov_b64_e32 v[56:57], v[8:9]
	v_mov_b64_e32 v[54:55], v[6:7]
	v_mov_b64_e32 v[52:53], v[4:5]
	v_mov_b64_e32 v[50:51], v[2:3]
	v_mov_b64_e32 v[48:49], v[0:1]
	v_mov_b64_e32 v[44:45], v[12:13]
	v_mov_b64_e32 v[42:43], v[10:11]
	v_mov_b64_e32 v[40:41], v[8:9]
	v_mov_b64_e32 v[38:39], v[6:7]
	v_mov_b64_e32 v[36:37], v[4:5]
	v_mov_b64_e32 v[34:35], v[2:3]
	v_mov_b64_e32 v[32:33], v[0:1]
	v_mov_b64_e32 v[28:29], v[12:13]
	v_mov_b64_e32 v[26:27], v[10:11]
	v_mov_b64_e32 v[24:25], v[8:9]
	v_mov_b64_e32 v[22:23], v[6:7]
	v_mov_b64_e32 v[20:21], v[4:5]
	v_mov_b64_e32 v[18:19], v[2:3]
	v_mov_b64_e32 v[16:17], v[0:1]
	s_branch .LBB0_364

.LBB0_373:
	s_cmp_gt_i32 s34, s52
	s_cbranch_scc1 .LBB0_363
	s_and_b32 s28, s34, 3
	s_mulk_i32 s28, 0x6000
	s_add_i32 s28, s28, 0
	v_add3_u32 v14, s28, v174, v173
	v_add3_u32 v15, s28, v174, v177
	ds_read_b128 v[2:5], v14
	ds_read_b128 v[6:9], v14 offset:4096
	ds_read_b128 v[10:13], v15
	ds_read_b128 v[252:255], v15 offset:4096
	v_add3_u32 v14, s28, v174, v179
	v_add3_u32 v15, s28, v174, v180
	ds_read_b128 v[156:159], v14
	ds_read_b128 v[160:163], v14 offset:4096
	ds_read_b128 v[244:247], v15
	ds_read_b128 v[248:251], v15 offset:4096
	s_waitcnt lgkmcnt(6)
	v_mfma_f32_32x32x16_bf16 v[96:111], v[2:5], v[112:115], 0
	v_mfma_f32_32x32x16_bf16 v[80:95], v[6:9], v[112:115], 0
	s_waitcnt lgkmcnt(4)
	v_mfma_f32_32x32x16_bf16 v[96:111], v[10:13], v[116:119], v[96:111]
	v_mfma_f32_32x32x16_bf16 v[80:95], v[252:255], v[116:119], v[80:95]
	s_waitcnt lgkmcnt(2)
	v_mfma_f32_32x32x16_bf16 v[96:111], v[156:159], v[120:123], v[96:111]
	v_mfma_f32_32x32x16_bf16 v[80:95], v[160:163], v[120:123], v[80:95]
	s_waitcnt lgkmcnt(0)
	v_mfma_f32_32x32x16_bf16 v[80:95], v[248:251], v[124:127], v[80:95]
	v_mfma_f32_32x32x16_bf16 v[96:111], v[244:247], v[124:127], v[96:111]
	s_nop 10
	v_max3_f32 v0, v80, v81, v82
	v_max3_f32 v2, v83, v84, v85
	v_max3_f32 v3, v86, v87, v88
	v_max3_f32 v4, v89, v90, v91
	v_max3_f32 v0, v0, v92, v93
	v_max3_f32 v2, v2, v94, v95
	v_max3_f32 v3, v3, v96, v97
	v_max3_f32 v4, v4, v98, v99
	v_max3_f32 v0, v0, v100, v101
	v_max3_f32 v2, v2, v102, v103
	v_max3_f32 v3, v3, v104, v105
	v_max3_f32 v4, v4, v106, v107
	v_max3_f32 v0, v0, v108, v109
	v_max3_f32 v2, v2, v110, v111
	v_max3_f32 v0, v0, v3, v4
	v_max_f32_e32 v0, v0, v2
	v_mov_b32_e32 v2, v0
	s_nop 1
	v_permlane32_swap_b32_e32 v0, v2
	v_max_f32_e32 v0, v0, v2
	v_cmp_gt_f32_e32 vcc, v0, v242
	s_cbranch_vccz .LBB0_362
	v_mul_f32_e32 v0, 0x3e38aa3b, v0
	v_max_f32_e32 v0, v0, v0
	v_max_f32_e32 v2, v150, v150
	v_max_f32_e32 v2, v2, v0
	v_sub_f32_e32 v0, v150, v2
	v_exp_f32_e32 v0, v0
	v_mov_b32_e32 v150, v2
	v_add_f32_e32 v2, 0x41000000, v2
	v_mul_f32_e32 v242, 0x40b17218, v2
	v_pk_mul_f32 v[30:31], v[30:31], v[0:1] op_sel_hi:[1,0]
	v_pk_mul_f32 v[28:29], v[28:29], v[0:1] op_sel_hi:[1,0]
	v_pk_mul_f32 v[26:27], v[26:27], v[0:1] op_sel_hi:[1,0]
	v_pk_mul_f32 v[24:25], v[24:25], v[0:1] op_sel_hi:[1,0]
	v_pk_mul_f32 v[22:23], v[22:23], v[0:1] op_sel_hi:[1,0]
	v_pk_mul_f32 v[20:21], v[20:21], v[0:1] op_sel_hi:[1,0]
	v_pk_mul_f32 v[18:19], v[18:19], v[0:1] op_sel_hi:[1,0]
	v_pk_mul_f32 v[16:17], v[16:17], v[0:1] op_sel_hi:[1,0]
	v_pk_mul_f32 v[46:47], v[46:47], v[0:1] op_sel_hi:[1,0]
	v_pk_mul_f32 v[44:45], v[44:45], v[0:1] op_sel_hi:[1,0]
	v_pk_mul_f32 v[42:43], v[42:43], v[0:1] op_sel_hi:[1,0]
	v_pk_mul_f32 v[40:41], v[40:41], v[0:1] op_sel_hi:[1,0]
	v_pk_mul_f32 v[38:39], v[38:39], v[0:1] op_sel_hi:[1,0]
	v_pk_mul_f32 v[36:37], v[36:37], v[0:1] op_sel_hi:[1,0]
	v_pk_mul_f32 v[34:35], v[34:35], v[0:1] op_sel_hi:[1,0]
	v_pk_mul_f32 v[32:33], v[32:33], v[0:1] op_sel_hi:[1,0]
	v_pk_mul_f32 v[62:63], v[62:63], v[0:1] op_sel_hi:[1,0]
	v_pk_mul_f32 v[60:61], v[60:61], v[0:1] op_sel_hi:[1,0]
	v_pk_mul_f32 v[58:59], v[58:59], v[0:1] op_sel_hi:[1,0]
	v_pk_mul_f32 v[56:57], v[56:57], v[0:1] op_sel_hi:[1,0]
	v_pk_mul_f32 v[54:55], v[54:55], v[0:1] op_sel_hi:[1,0]
	v_pk_mul_f32 v[52:53], v[52:53], v[0:1] op_sel_hi:[1,0]
	v_pk_mul_f32 v[50:51], v[50:51], v[0:1] op_sel_hi:[1,0]
	v_pk_mul_f32 v[48:49], v[48:49], v[0:1] op_sel_hi:[1,0]
	v_pk_mul_f32 v[78:79], v[78:79], v[0:1] op_sel_hi:[1,0]
	v_pk_mul_f32 v[76:77], v[76:77], v[0:1] op_sel_hi:[1,0]
	v_pk_mul_f32 v[74:75], v[74:75], v[0:1] op_sel_hi:[1,0]
	v_pk_mul_f32 v[72:73], v[72:73], v[0:1] op_sel_hi:[1,0]
	v_pk_mul_f32 v[70:71], v[70:71], v[0:1] op_sel_hi:[1,0]
	v_pk_mul_f32 v[68:69], v[68:69], v[0:1] op_sel_hi:[1,0]
	v_pk_mul_f32 v[66:67], v[66:67], v[0:1] op_sel_hi:[1,0]
	v_pk_mul_f32 v[64:65], v[64:65], v[0:1] op_sel_hi:[1,0]
	v_mul_f32_e32 v154, v154, v0
	s_branch .LBB0_362
